# static s_setprio 1 for waves 0-3 (loader waves) at kernel entry
# baseline (speedup 1.0000x reference)
; DEV int vhalf() { return __builtin_amdgcn_readfirstlane((int)(threadIdx.x >> 8)); }
; #define LAS __attribute__((address_space(3)))
; __global__ void __launch_bounds__(512) mk(Params p) {
;   cg::grid_group grid = cg::this_grid();
;   __shared__ __attribute__((aligned(16))) char smem[SMEM_BYTES];
;   __shared__ uint4 xb_words;
;   if (threadIdx.x == 0) xb_words = make_uint4(0u, 0u, 0u, 0u);
;   __syncthreads();
;   const XcdBarrier xb = xcd_barrier_post((unsigned*)(p.ws + OFF_XBAR), (volatile LAS unsigned*)&xb_words);
;   char* hsm = smem + vhalf() * HALF_BYTES;
_Z2mk6Params:
	s_load_dwordx4 s[88:91], s[0:1], 0xe0
	s_load_dwordx8 s[72:79], s[0:1], 0xc0
	s_add_u32 s10, s0, 0xe8
	v_and_b32_e32 v202, 0x3ff, v0
	s_mov_b32 s80, s2
	s_addc_u32 s11, s1, 0
	v_readfirstlane_b32 s100, v202
	s_nop 3
	s_lshr_b32 s100, s100, 6
	s_cmp_ge_u32 s100, 4
	s_cbranch_scc1 .Lprio_done
	s_setprio 1
